# first K-loop iteration of the W_in, gate/up and down GEMM phases peeled: its first-touch MFMAs take C = 0, so the 127 v_mov accumulator zeroing in front of every unit disappears
# speedup vs baseline: 1.0042x; 1.0042x over previous
; #define PG8_STAGE(bufoff, gbase, voff) do { _Pragma("unroll") for (int _i = 0; _i < 2; ++_i) \
;         __builtin_amdgcn_global_load_lds((const unsigned*)((const char*)(gbase) + (voff)[_i]), (PG8_LAS unsigned*)(lds + (bufoff) + ldsw + _i * 8192), 16, 0, 0); } while (0)
; #define PG8_LDA(dst, b, h) do { _Pragma("unroll") for (int m = 0; m < 4; ++m) _Pragma("unroll") for (int k = 0; k < 2; ++k) dst[m][k] = *(const PG8_LAS bf16x8*)(lds + PG8_SA(b, h) + aoff + m * 2048 + k * 1024); } while (0)
; #define PG8_LDB(dst, b, h) do { _Pragma("unroll") for (int n = 0; n < 2; ++n) _Pragma("unroll") for (int k = 0; k < 2; ++k) dst[n][k] = *(const PG8_LAS bf16x8*)(lds + PG8_SB(b, h) + boff + n * 2048 + k * 1024); } while (0)
; #define PG8_MMA(ai, bj, At, Bt) do { __builtin_amdgcn_s_setprio(1); _Pragma("unroll") for (int m = 0; m < 4; ++m) _Pragma("unroll") for (int n = 0; n < 2; ++n) _Pragma("unroll") for (int k = 0; k < 2; ++k) \
;         acc[ai][bj][m][n] = __builtin_amdgcn_mfma_f32_16x16x32_bf16(Bt[n][k], At[m][k], acc[ai][bj][m][n], 0, 0, 0); __builtin_amdgcn_s_setprio(0); } while (0)
; #define PG8_WAIT_V(n) asm volatile("s_waitcnt vmcnt(" #n ")" ::: "memory")
; template <class Epi, class Sched, bool ALIGN_EPI = false, bool SP2 = false>
; __device__ __forceinline__ void gemm_phase(PG8_LAS unsigned char* lds, const Gemm g, const Sched& S, const Epi& E) {
;     ...
;         const bool has_next = S.next(ui + 1, nxt);
;         const char* nA = has_next ? (const char*)g.A + (size_t)nxt.pm * tstep : cA; const char* nB = has_next ? (const char*)g.Bt + (size_t)nxt.pn * tstep : cB;
;         for (int t = 0; t < nt; t += 2) {
;             const bool last = (t == nt - 2);
;             const char* a1 = cA + (size_t)(t + 1) * kstep;
;             const char* a2 = last ? nA : cA + (size_t)(t + 2) * kstep; const char* b2 = last ? nB : cB + (size_t)(t + 2) * kstep;
;             const char* a3 = a2 + kstep; const char* b3 = b2 + kstep;
;             if (last && has_next) S.a_ready(nxt);
;             if constexpr (Epi::KSPLIT) { if (t == (nt >> 1)) E.mid(acc, cur, wr, wc, fr, fq); }
;             if constexpr (SP2) {
;             PG8_LDB(B0, 0, 0); PG8_LDB(B1, 0, 1); PG8_SCHED; PG8_LDA(At, 0, 0); PG8_STAGE(PG8_SA(1, 1), a1 + hstep, voffA);
;             PG8_WAIT_V(8); PG8_WAIT_L(0); PG8_BAR; PG8_MMA(0, 0, At, B0); PG8_MMA(0, 1, At, B1); PG8_BAR; PG8_SCHED;
.LBB0_173:
	s_add_i32 s51, s51, 1
	s_mov_b64 s[2:3], s[6:7]
	s_mov_b32 s53, s14
	s_lshl_b32 s6, s51, 3
	v_readlane_b32 s14, v248, 25
	s_add_i32 s14, s6, s14
	v_readlane_b32 s15, v248, 26
	s_cmp_lt_i32 s14, 14
	s_cselect_b64 s[38:39], -1, 0
	s_ashr_i32 s15, s14, 31
	s_lshl_b64 s[6:7], s[14:15], 20
	s_add_u32 s6, s44, s6
	s_addc_u32 s7, s45, s7
	s_and_b64 s[36:37], s[38:39], exec
	v_mov_b32_e32 v4, 0
	s_cselect_b32 s15, s7, s3
	s_cselect_b32 s52, s6, s2
	s_mov_b32 s54, -2
	s_mov_b64 s[2:3], 0
	v_add_u32_e32 v168, 0x10000, v3
	v_add_u32_e32 v169, 0x14000, v3
	v_add_u32_e32 v170, 0x18000, v3
	v_add_u32_e32 v171, 0x1c000, v3
	s_cmp_lg_u64 s[10:11], 0
	s_cbranch_scc1 .Lprio_P1
	s_setprio 1
.Lprio_P1:
	s_add_u32 s36, s31, s2
	s_addc_u32 s37, s91, s3
	s_add_u32 s36, s36, 0x16200100
	s_addc_u32 s37, s37, 0
	s_add_u32 s55, s12, s2
	s_addc_u32 s56, s13, s3
	s_add_i32 s57, 0, 0x10000
	s_cmpk_eq_i32 s2, 0xf00
	s_cselect_b32 s41, s1, s37
	s_cselect_b32 s40, s0, s36
	s_cselect_b32 s37, s15, s56
	s_cselect_b32 s36, s52, s55
	s_add_i32 s55, 0, 0x14000
	ds_read_b128 v[142:145], v168
	ds_read_b128 v[146:149], v168 offset:1024
	ds_read_b128 v[156:159], v168 offset:2048
	ds_read_b128 v[172:175], v168 offset:3072
	ds_read_b128 v[176:179], v169
	ds_read_b128 v[180:183], v169 offset:1024
	ds_read_b128 v[184:187], v169 offset:2048
	ds_read_b128 v[188:191], v169 offset:3072
	v_lshl_add_u64 v[150:151], v[138:139], 0, s[2:3]
	s_add_i32 m0, s43, 0xc000
	ds_read_b128 v[192:195], v154
	ds_read_b128 v[196:199], v154 offset:1024
	ds_read_b128 v[200:203], v154 offset:2048
	ds_read_b128 v[212:215], v154 offset:3072
	ds_read_b128 v[216:219], v154 offset:4096
	ds_read_b128 v[220:223], v154 offset:5120
	ds_read_b128 v[224:227], v154 offset:6144
	ds_read_b128 v[228:231], v154 offset:7168
	global_load_lds_dwordx4 v[150:151], off
	v_lshl_add_u64 v[150:151], v[140:141], 0, s[2:3]
	s_add_i32 m0, s43, 0xe000
	s_nop 0
	global_load_lds_dwordx4 v[150:151], off
	s_waitcnt vmcnt(8)
	s_waitcnt lgkmcnt(0)
	s_barrier
	s_waitcnt lgkmcnt(0)
	v_mfma_f32_16x16x32_bf16 v[128:131], v[142:145], v[192:195], 0
	v_mfma_f32_16x16x32_bf16 v[124:127], v[156:159], v[192:195], 0
	v_mfma_f32_16x16x32_bf16 v[112:115], v[142:145], v[200:203], 0
	v_mfma_f32_16x16x32_bf16 v[108:111], v[156:159], v[200:203], 0
	v_mfma_f32_16x16x32_bf16 v[96:99], v[142:145], v[216:219], 0
	v_mfma_f32_16x16x32_bf16 v[92:95], v[156:159], v[216:219], 0
	v_mfma_f32_16x16x32_bf16 v[80:83], v[142:145], v[224:227], 0
	v_mfma_f32_16x16x32_bf16 v[76:79], v[156:159], v[224:227], 0
	v_mfma_f32_16x16x32_bf16 v[128:131], v[146:149], v[196:199], v[128:131]
	v_mfma_f32_16x16x32_bf16 v[124:127], v[172:175], v[196:199], v[124:127]
	v_mfma_f32_16x16x32_bf16 v[112:115], v[146:149], v[212:215], v[112:115]
	v_mfma_f32_16x16x32_bf16 v[108:111], v[172:175], v[212:215], v[108:111]
	v_mfma_f32_16x16x32_bf16 v[96:99], v[146:149], v[220:223], v[96:99]
	v_mfma_f32_16x16x32_bf16 v[92:95], v[172:175], v[220:223], v[92:95]
	v_mfma_f32_16x16x32_bf16 v[80:83], v[146:149], v[228:231], v[80:83]
	v_mfma_f32_16x16x32_bf16 v[76:79], v[172:175], v[228:231], v[76:79]
	v_mfma_f32_16x16x32_bf16 v[120:123], v[176:179], v[192:195], 0
	v_mfma_f32_16x16x32_bf16 v[116:119], v[184:187], v[192:195], 0
	v_mfma_f32_16x16x32_bf16 v[104:107], v[176:179], v[200:203], 0
	v_mfma_f32_16x16x32_bf16 v[100:103], v[184:187], v[200:203], 0
	v_mfma_f32_16x16x32_bf16 v[88:91], v[176:179], v[216:219], 0
	v_mfma_f32_16x16x32_bf16 v[84:87], v[184:187], v[216:219], 0
	v_mfma_f32_16x16x32_bf16 v[72:75], v[176:179], v[224:227], 0
	v_mfma_f32_16x16x32_bf16 v[68:71], v[184:187], v[224:227], 0
	v_mfma_f32_16x16x32_bf16 v[120:123], v[180:183], v[196:199], v[120:123]
	v_mfma_f32_16x16x32_bf16 v[116:119], v[188:191], v[196:199], v[116:119]
	v_mfma_f32_16x16x32_bf16 v[104:107], v[180:183], v[212:215], v[104:107]
	v_mfma_f32_16x16x32_bf16 v[100:103], v[188:191], v[212:215], v[100:103]
	v_mfma_f32_16x16x32_bf16 v[88:91], v[180:183], v[220:223], v[88:91]
	v_mfma_f32_16x16x32_bf16 v[84:87], v[188:191], v[220:223], v[84:87]
	v_mfma_f32_16x16x32_bf16 v[72:75], v[180:183], v[228:231], v[72:75]
	v_mfma_f32_16x16x32_bf16 v[68:71], v[188:191], v[228:231], v[68:71]
	s_barrier
	s_add_i32 s56, s57, s42
	s_add_u32 s98, s36, 0x80
	s_addc_u32 s99, s37, 0
	s_mov_b32 m0, s56
	ds_read_b128 v[192:195], v154 offset:16384
	ds_read_b128 v[196:199], v154 offset:17408
	ds_read_b128 v[200:203], v154 offset:18432
	ds_read_b128 v[212:215], v154 offset:19456
	ds_read_b128 v[216:219], v154 offset:20480
	ds_read_b128 v[220:223], v154 offset:21504
	ds_read_b128 v[224:227], v154 offset:22528
	ds_read_b128 v[228:231], v154 offset:23552
	global_load_lds_dwordx4 v134, s[36:37]
	s_add_i32 m0, s56, 0x2000
	s_add_u32 s56, s36, 0x80000
	s_addc_u32 s57, s37, 0
	s_add_i32 s55, s55, s42
	global_load_lds_dwordx4 v0, s[36:37]
	s_mov_b32 m0, s55
	s_add_u32 s100, s40, 0x80
	s_addc_u32 s101, s41, 0
	s_nop 0
	global_load_lds_dwordx4 v134, s[56:57]
	s_add_i32 m0, s55, 0x2000
	s_nop 0
	global_load_lds_dwordx4 v0, s[56:57]
	s_mov_b32 m0, s43
	s_nop 0
	global_load_lds_dwordx4 v136, s[40:41]
	s_mov_b32 m0, s46
	s_nop 0
	global_load_lds_dwordx4 v132, s[40:41]
	s_waitcnt vmcnt(8)
	s_waitcnt lgkmcnt(0)
	s_barrier
; #define PG8_STAGE(bufoff, gbase, voff) do { _Pragma("unroll") for (int _i = 0; _i < 2; ++_i) \
;         __builtin_amdgcn_global_load_lds((const unsigned*)((const char*)(gbase) + (voff)[_i]), (PG8_LAS unsigned*)(lds + (bufoff) + ldsw + _i * 8192), 16, 0, 0); } while (0)
; #define PG8_LDA(dst, b, h) do { _Pragma("unroll") for (int m = 0; m < 4; ++m) _Pragma("unroll") for (int k = 0; k < 2; ++k) dst[m][k] = *(const PG8_LAS bf16x8*)(lds + PG8_SA(b, h) + aoff + m * 2048 + k * 1024); } while (0)
; #define PG8_LDB(dst, b, h) do { _Pragma("unroll") for (int n = 0; n < 2; ++n) _Pragma("unroll") for (int k = 0; k < 2; ++k) dst[n][k] = *(const PG8_LAS bf16x8*)(lds + PG8_SB(b, h) + boff + n * 2048 + k * 1024); } while (0)
; #define PG8_MMA(ai, bj, At, Bt) do { __builtin_amdgcn_s_setprio(1); _Pragma("unroll") for (int m = 0; m < 4; ++m) _Pragma("unroll") for (int n = 0; n < 2; ++n) _Pragma("unroll") for (int k = 0; k < 2; ++k) \
;         acc[ai][bj][m][n] = __builtin_amdgcn_mfma_f32_16x16x32_bf16(Bt[n][k], At[m][k], acc[ai][bj][m][n], 0, 0, 0); __builtin_amdgcn_s_setprio(0); } while (0)
; #define PG8_WAIT_V(n) asm volatile("s_waitcnt vmcnt(" #n ")" ::: "memory")
; #define PG8_WAIT_L(n) asm volatile("s_waitcnt lgkmcnt(" #n ")" ::: "memory")
; #define PG8_BAR __builtin_amdgcn_s_barrier()
; #define PG8_SCHED __builtin_amdgcn_sched_barrier(0)
; template <class Epi, class Sched, bool ALIGN_EPI = false, bool SP2 = false>
; __device__ __forceinline__ void gemm_phase(PG8_LAS unsigned char* lds, const Gemm g, const Sched& S, const Epi& E) {
;     ...
;             PG8_WAIT_V(8); PG8_WAIT_L(0); PG8_BAR; PG8_MMA(0, 0, At, B0); PG8_MMA(0, 1, At, B1); PG8_BAR; PG8_SCHED;
;             PG8_LDA(At, 0, 1); PG8_STAGE(PG8_SB(0, 0), b2, voffB); PG8_STAGE(PG8_SB(0, 1), b2 + hstep, voffB); PG8_STAGE(PG8_SA(0, 0), a2, voffA);
;             PG8_WAIT_V(8); PG8_WAIT_L(0); PG8_BAR; PG8_MMA(1, 0, At, B0); PG8_MMA(1, 1, At, B1); PG8_BAR; PG8_SCHED;
;             PG8_LDB(B0, 1, 0); PG8_LDB(B1, 1, 1); PG8_SCHED; PG8_LDA(At, 1, 0); PG8_STAGE(PG8_SA(0, 1), a2 + hstep, voffA);
;             PG8_WAIT_V(8); PG8_WAIT_L(0); PG8_BAR; PG8_MMA(0, 0, At, B0); PG8_MMA(0, 1, At, B1); PG8_BAR; PG8_SCHED;
	s_waitcnt lgkmcnt(0)
	v_mfma_f32_16x16x32_bf16 v[64:67], v[142:145], v[192:195], 0
	v_mfma_f32_16x16x32_bf16 v[60:63], v[156:159], v[192:195], 0
	v_mfma_f32_16x16x32_bf16 v[48:51], v[142:145], v[200:203], 0
	v_mfma_f32_16x16x32_bf16 v[44:47], v[156:159], v[200:203], 0
	v_mfma_f32_16x16x32_bf16 v[32:35], v[142:145], v[216:219], 0
	v_mfma_f32_16x16x32_bf16 v[28:31], v[156:159], v[216:219], 0
	v_mfma_f32_16x16x32_bf16 v[16:19], v[142:145], v[224:227], 0
	v_mfma_f32_16x16x32_bf16 v[12:15], v[156:159], v[224:227], 0
	v_mfma_f32_16x16x32_bf16 v[64:67], v[146:149], v[196:199], v[64:67]
	v_mfma_f32_16x16x32_bf16 v[60:63], v[172:175], v[196:199], v[60:63]
	v_mfma_f32_16x16x32_bf16 v[48:51], v[146:149], v[212:215], v[48:51]
	v_mfma_f32_16x16x32_bf16 v[44:47], v[172:175], v[212:215], v[44:47]
	v_mfma_f32_16x16x32_bf16 v[32:35], v[146:149], v[220:223], v[32:35]
	v_mfma_f32_16x16x32_bf16 v[28:31], v[172:175], v[220:223], v[28:31]
	v_mfma_f32_16x16x32_bf16 v[16:19], v[146:149], v[228:231], v[16:19]
	v_mfma_f32_16x16x32_bf16 v[12:15], v[172:175], v[228:231], v[12:15]
	v_mfma_f32_16x16x32_bf16 v[56:59], v[176:179], v[192:195], 0
	v_mfma_f32_16x16x32_bf16 v[52:55], v[184:187], v[192:195], 0
	v_mfma_f32_16x16x32_bf16 v[40:43], v[176:179], v[200:203], 0
	v_mfma_f32_16x16x32_bf16 v[36:39], v[184:187], v[200:203], 0
	v_mfma_f32_16x16x32_bf16 v[24:27], v[176:179], v[216:219], 0
	v_mfma_f32_16x16x32_bf16 v[20:23], v[184:187], v[216:219], 0
	v_mfma_f32_16x16x32_bf16 v[8:11], v[176:179], v[224:227], 0
	v_mfma_f32_16x16x32_bf16 v[4:7], v[184:187], v[224:227], 0
	v_mfma_f32_16x16x32_bf16 v[56:59], v[180:183], v[196:199], v[56:59]
	v_mfma_f32_16x16x32_bf16 v[52:55], v[188:191], v[196:199], v[52:55]
	v_mfma_f32_16x16x32_bf16 v[40:43], v[180:183], v[212:215], v[40:43]
	v_mfma_f32_16x16x32_bf16 v[36:39], v[188:191], v[212:215], v[36:39]
	v_mfma_f32_16x16x32_bf16 v[24:27], v[180:183], v[220:223], v[24:27]
	v_mfma_f32_16x16x32_bf16 v[20:23], v[188:191], v[220:223], v[20:23]
	v_mfma_f32_16x16x32_bf16 v[8:11], v[180:183], v[228:231], v[8:11]
	v_mfma_f32_16x16x32_bf16 v[4:7], v[188:191], v[228:231], v[4:7]
	s_barrier
	s_add_i32 s55, 0, 0x18000
	s_add_i32 s56, 0, 0x1c000
	ds_read_b128 v[142:145], v170
	ds_read_b128 v[146:149], v170 offset:1024
	ds_read_b128 v[156:159], v170 offset:2048
	ds_read_b128 v[172:175], v170 offset:3072
	ds_read_b128 v[176:179], v171
	ds_read_b128 v[180:183], v171 offset:1024
	ds_read_b128 v[184:187], v171 offset:2048
	ds_read_b128 v[188:191], v171 offset:3072
	s_add_u32 s40, s40, 0x80000
	s_addc_u32 s41, s41, 0
	s_mov_b32 m0, s47
	ds_read_b128 v[192:195], v154 offset:32768
	ds_read_b128 v[196:199], v154 offset:33792
	ds_read_b128 v[200:203], v154 offset:34816
	ds_read_b128 v[212:215], v154 offset:35840
	ds_read_b128 v[216:219], v154 offset:36864
	ds_read_b128 v[220:223], v154 offset:37888
	ds_read_b128 v[224:227], v154 offset:38912
	ds_read_b128 v[228:231], v154 offset:39936
	global_load_lds_dwordx4 v136, s[40:41]
	s_mov_b32 m0, s48
	s_nop 0
	global_load_lds_dwordx4 v132, s[40:41]
	s_waitcnt vmcnt(8)
	s_waitcnt lgkmcnt(0)
	s_barrier
	s_waitcnt lgkmcnt(0)
	v_mfma_f32_16x16x32_bf16 v[128:131], v[142:145], v[192:195], v[128:131]
	v_mfma_f32_16x16x32_bf16 v[124:127], v[156:159], v[192:195], v[124:127]
	v_mfma_f32_16x16x32_bf16 v[112:115], v[142:145], v[200:203], v[112:115]
	v_mfma_f32_16x16x32_bf16 v[108:111], v[156:159], v[200:203], v[108:111]
	v_mfma_f32_16x16x32_bf16 v[96:99], v[142:145], v[216:219], v[96:99]
	v_mfma_f32_16x16x32_bf16 v[92:95], v[156:159], v[216:219], v[92:95]
	v_mfma_f32_16x16x32_bf16 v[80:83], v[142:145], v[224:227], v[80:83]
	v_mfma_f32_16x16x32_bf16 v[76:79], v[156:159], v[224:227], v[76:79]
	v_mfma_f32_16x16x32_bf16 v[128:131], v[146:149], v[196:199], v[128:131]
	v_mfma_f32_16x16x32_bf16 v[124:127], v[172:175], v[196:199], v[124:127]
	v_mfma_f32_16x16x32_bf16 v[112:115], v[146:149], v[212:215], v[112:115]
	v_mfma_f32_16x16x32_bf16 v[108:111], v[172:175], v[212:215], v[108:111]
	v_mfma_f32_16x16x32_bf16 v[96:99], v[146:149], v[220:223], v[96:99]
	v_mfma_f32_16x16x32_bf16 v[92:95], v[172:175], v[220:223], v[92:95]
	v_mfma_f32_16x16x32_bf16 v[80:83], v[146:149], v[228:231], v[80:83]
	v_mfma_f32_16x16x32_bf16 v[76:79], v[172:175], v[228:231], v[76:79]
	v_mfma_f32_16x16x32_bf16 v[120:123], v[176:179], v[192:195], v[120:123]
	v_mfma_f32_16x16x32_bf16 v[116:119], v[184:187], v[192:195], v[116:119]
	v_mfma_f32_16x16x32_bf16 v[104:107], v[176:179], v[200:203], v[104:107]
	v_mfma_f32_16x16x32_bf16 v[100:103], v[184:187], v[200:203], v[100:103]
	v_mfma_f32_16x16x32_bf16 v[88:91], v[176:179], v[216:219], v[88:91]
	v_mfma_f32_16x16x32_bf16 v[84:87], v[184:187], v[216:219], v[84:87]
	v_mfma_f32_16x16x32_bf16 v[72:75], v[176:179], v[224:227], v[72:75]
	v_mfma_f32_16x16x32_bf16 v[68:71], v[184:187], v[224:227], v[68:71]
	v_mfma_f32_16x16x32_bf16 v[120:123], v[180:183], v[196:199], v[120:123]
	v_mfma_f32_16x16x32_bf16 v[116:119], v[188:191], v[196:199], v[116:119]
	v_mfma_f32_16x16x32_bf16 v[104:107], v[180:183], v[212:215], v[104:107]
	v_mfma_f32_16x16x32_bf16 v[100:103], v[188:191], v[212:215], v[100:103]
	v_mfma_f32_16x16x32_bf16 v[88:91], v[180:183], v[220:223], v[88:91]
	v_mfma_f32_16x16x32_bf16 v[84:87], v[188:191], v[220:223], v[84:87]
	v_mfma_f32_16x16x32_bf16 v[72:75], v[180:183], v[228:231], v[72:75]
	v_mfma_f32_16x16x32_bf16 v[68:71], v[188:191], v[228:231], v[68:71]
	s_barrier
; #define PG8_STAGE(bufoff, gbase, voff) do { _Pragma("unroll") for (int _i = 0; _i < 2; ++_i) \
;         __builtin_amdgcn_global_load_lds((const unsigned*)((const char*)(gbase) + (voff)[_i]), (PG8_LAS unsigned*)(lds + (bufoff) + ldsw + _i * 8192), 16, 0, 0); } while (0)
; #define PG8_LDA(dst, b, h) do { _Pragma("unroll") for (int m = 0; m < 4; ++m) _Pragma("unroll") for (int k = 0; k < 2; ++k) dst[m][k] = *(const PG8_LAS bf16x8*)(lds + PG8_SA(b, h) + aoff + m * 2048 + k * 1024); } while (0)
; #define PG8_MMA(ai, bj, At, Bt) do { __builtin_amdgcn_s_setprio(1); _Pragma("unroll") for (int m = 0; m < 4; ++m) _Pragma("unroll") for (int n = 0; n < 2; ++n) _Pragma("unroll") for (int k = 0; k < 2; ++k) \
;         acc[ai][bj][m][n] = __builtin_amdgcn_mfma_f32_16x16x32_bf16(Bt[n][k], At[m][k], acc[ai][bj][m][n], 0, 0, 0); __builtin_amdgcn_s_setprio(0); } while (0)
; #define PG8_WAIT_V(n) asm volatile("s_waitcnt vmcnt(" #n ")" ::: "memory")
; #define PG8_WAIT_L(n) asm volatile("s_waitcnt lgkmcnt(" #n ")" ::: "memory")
; #define PG8_BAR __builtin_amdgcn_s_barrier()
; #define PG8_SCHED __builtin_amdgcn_sched_barrier(0)
; template <class Epi, class Sched, bool ALIGN_EPI = false, bool SP2 = false>
; __device__ __forceinline__ void gemm_phase(PG8_LAS unsigned char* lds, const Gemm g, const Sched& S, const Epi& E) {
;     ...
;             PG8_LDA(At, 1, 1); PG8_STAGE(PG8_SB(1, 0), b3, voffB); PG8_STAGE(PG8_SB(1, 1), b3 + hstep, voffB); PG8_STAGE(PG8_SA(1, 0), a3, voffA);
;             PG8_WAIT_V(8); PG8_WAIT_L(0); PG8_BAR; PG8_MMA(1, 0, At, B0); PG8_MMA(1, 1, At, B1); PG8_BAR; PG8_SCHED;
	s_add_i32 s40, s55, s42
	s_mov_b32 m0, s40
	ds_read_b128 v[192:195], v154 offset:49152
	ds_read_b128 v[196:199], v154 offset:50176
	ds_read_b128 v[200:203], v154 offset:51200
	ds_read_b128 v[212:215], v154 offset:52224
	ds_read_b128 v[216:219], v154 offset:53248
	ds_read_b128 v[220:223], v154 offset:54272
	ds_read_b128 v[224:227], v154 offset:55296
	ds_read_b128 v[228:231], v154 offset:56320
	global_load_lds_dwordx4 v134, s[98:99]
	s_add_i32 m0, s40, 0x2000
	s_add_u32 s36, s36, 0x80080
	s_addc_u32 s37, s37, 0
	s_add_i32 s40, s56, s42
	global_load_lds_dwordx4 v0, s[98:99]
	s_mov_b32 m0, s40
	s_nop 0
	global_load_lds_dwordx4 v134, s[36:37]
	s_add_i32 m0, s40, 0x2000
	s_nop 0
	global_load_lds_dwordx4 v0, s[36:37]
	s_mov_b32 m0, s49
	s_nop 0
	global_load_lds_dwordx4 v136, s[100:101]
	s_mov_b32 m0, s50
	s_nop 0
	global_load_lds_dwordx4 v132, s[100:101]
	s_waitcnt vmcnt(8)
	s_waitcnt lgkmcnt(0)
	s_barrier
	s_waitcnt lgkmcnt(0)
	v_mfma_f32_16x16x32_bf16 v[64:67], v[142:145], v[192:195], v[64:67]
	v_mfma_f32_16x16x32_bf16 v[60:63], v[156:159], v[192:195], v[60:63]
	v_mfma_f32_16x16x32_bf16 v[48:51], v[142:145], v[200:203], v[48:51]
	v_mfma_f32_16x16x32_bf16 v[44:47], v[156:159], v[200:203], v[44:47]
	v_mfma_f32_16x16x32_bf16 v[32:35], v[142:145], v[216:219], v[32:35]
	v_mfma_f32_16x16x32_bf16 v[28:31], v[156:159], v[216:219], v[28:31]
	v_mfma_f32_16x16x32_bf16 v[16:19], v[142:145], v[224:227], v[16:19]
	v_mfma_f32_16x16x32_bf16 v[12:15], v[156:159], v[224:227], v[12:15]
	v_mfma_f32_16x16x32_bf16 v[64:67], v[146:149], v[196:199], v[64:67]
	v_mfma_f32_16x16x32_bf16 v[60:63], v[172:175], v[196:199], v[60:63]
	v_mfma_f32_16x16x32_bf16 v[48:51], v[146:149], v[212:215], v[48:51]
	v_mfma_f32_16x16x32_bf16 v[44:47], v[172:175], v[212:215], v[44:47]
	v_mfma_f32_16x16x32_bf16 v[32:35], v[146:149], v[220:223], v[32:35]
	v_mfma_f32_16x16x32_bf16 v[28:31], v[172:175], v[220:223], v[28:31]
	v_mfma_f32_16x16x32_bf16 v[16:19], v[146:149], v[228:231], v[16:19]
	v_mfma_f32_16x16x32_bf16 v[12:15], v[172:175], v[228:231], v[12:15]
	v_mfma_f32_16x16x32_bf16 v[56:59], v[176:179], v[192:195], v[56:59]
	v_mfma_f32_16x16x32_bf16 v[52:55], v[184:187], v[192:195], v[52:55]
	v_mfma_f32_16x16x32_bf16 v[40:43], v[176:179], v[200:203], v[40:43]
	v_mfma_f32_16x16x32_bf16 v[36:39], v[184:187], v[200:203], v[36:39]
	v_mfma_f32_16x16x32_bf16 v[24:27], v[176:179], v[216:219], v[24:27]
	v_mfma_f32_16x16x32_bf16 v[20:23], v[184:187], v[216:219], v[20:23]
	v_mfma_f32_16x16x32_bf16 v[8:11], v[176:179], v[224:227], v[8:11]
	v_mfma_f32_16x16x32_bf16 v[4:7], v[184:187], v[224:227], v[4:7]
	v_mfma_f32_16x16x32_bf16 v[56:59], v[180:183], v[196:199], v[56:59]
	v_mfma_f32_16x16x32_bf16 v[52:55], v[188:191], v[196:199], v[52:55]
	v_mfma_f32_16x16x32_bf16 v[40:43], v[180:183], v[212:215], v[40:43]
	v_mfma_f32_16x16x32_bf16 v[36:39], v[188:191], v[212:215], v[36:39]
	v_mfma_f32_16x16x32_bf16 v[24:27], v[180:183], v[220:223], v[24:27]
	v_mfma_f32_16x16x32_bf16 v[20:23], v[188:191], v[220:223], v[20:23]
	v_mfma_f32_16x16x32_bf16 v[8:11], v[180:183], v[228:231], v[8:11]
	v_mfma_f32_16x16x32_bf16 v[4:7], v[188:191], v[228:231], v[4:7]
	s_barrier
	s_add_i32 s54, s54, 2
	s_add_u32 s2, s2, 0x100
	s_addc_u32 s3, s3, 0
	s_cmp_gt_u32 s54, 29

; #define PG8_STAGE(bufoff, gbase, voff) do { _Pragma("unroll") for (int _i = 0; _i < 2; ++_i) \
;         __builtin_amdgcn_global_load_lds((const unsigned*)((const char*)(gbase) + (voff)[_i]), (PG8_LAS unsigned*)(lds + (bufoff) + ldsw + _i * 8192), 16, 0, 0); } while (0)
; #define PG8_LDA(dst, b, h) do { _Pragma("unroll") for (int m = 0; m < 4; ++m) _Pragma("unroll") for (int k = 0; k < 2; ++k) dst[m][k] = *(const PG8_LAS bf16x8*)(lds + PG8_SA(b, h) + aoff + m * 2048 + k * 1024); } while (0)
; #define PG8_LDB(dst, b, h) do { _Pragma("unroll") for (int n = 0; n < 2; ++n) _Pragma("unroll") for (int k = 0; k < 2; ++k) dst[n][k] = *(const PG8_LAS bf16x8*)(lds + PG8_SB(b, h) + boff + n * 2048 + k * 1024); } while (0)
; #define PG8_MMA(ai, bj, At, Bt) do { __builtin_amdgcn_s_setprio(1); _Pragma("unroll") for (int m = 0; m < 4; ++m) _Pragma("unroll") for (int n = 0; n < 2; ++n) _Pragma("unroll") for (int k = 0; k < 2; ++k) \
;         acc[ai][bj][m][n] = __builtin_amdgcn_mfma_f32_16x16x32_bf16(Bt[n][k], At[m][k], acc[ai][bj][m][n], 0, 0, 0); __builtin_amdgcn_s_setprio(0); } while (0)
; #define PG8_WAIT_V(n) asm volatile("s_waitcnt vmcnt(" #n ")" ::: "memory")
; template <class Epi, class Sched, bool ALIGN_EPI = false, bool SP2 = false>
; __device__ __forceinline__ void gemm_phase(PG8_LAS unsigned char* lds, const Gemm g, const Sched& S, const Epi& E) {
;     ...
;         const bool has_next = S.next(ui + 1, nxt);
;         const char* nA = has_next ? (const char*)g.A + (size_t)nxt.pm * tstep : cA; const char* nB = has_next ? (const char*)g.Bt + (size_t)nxt.pn * tstep : cB;
;         for (int t = 0; t < nt; t += 2) {
;             const bool last = (t == nt - 2);
;             const char* a1 = cA + (size_t)(t + 1) * kstep;
;             const char* a2 = last ? nA : cA + (size_t)(t + 2) * kstep; const char* b2 = last ? nB : cB + (size_t)(t + 2) * kstep;
;             const char* a3 = a2 + kstep; const char* b3 = b2 + kstep;
;             if (last && has_next) S.a_ready(nxt);
;             if constexpr (Epi::KSPLIT) { if (t == (nt >> 1)) E.mid(acc, cur, wr, wc, fr, fq); }
;             if constexpr (SP2) {
;             PG8_LDB(B0, 0, 0); PG8_LDB(B1, 0, 1); PG8_SCHED; PG8_LDA(At, 0, 0); PG8_STAGE(PG8_SA(1, 1), a1 + hstep, voffA);
;             PG8_WAIT_V(8); PG8_WAIT_L(0); PG8_BAR; PG8_MMA(0, 0, At, B0); PG8_MMA(0, 1, At, B1); PG8_BAR; PG8_SCHED;
.LBB0_1050:
	s_mov_b64 s[2:3], s[6:7]
	s_mov_b32 s6, s51
	s_add_i32 s51, s51, 1
	s_sub_i32 s7, 3, s6
	s_cmp_lt_u32 s6, 4
	s_cselect_b32 s6, s7, s51
	s_mov_b32 s52, s12
	s_lshl_b32 s6, s6, 3
	v_readlane_b32 s12, v248, 25
	s_add_i32 s12, s6, s12
	v_readlane_b32 s13, v248, 26
	s_cmp_lt_i32 s12, 44
	s_cselect_b64 s[14:15], -1, 0
	s_ashr_i32 s13, s12, 31
	s_lshl_b64 s[6:7], s[12:13], 20
	s_add_u32 s6, s46, s6
	s_addc_u32 s7, s47, s7
	s_and_b64 s[36:37], s[14:15], exec
	s_cselect_b32 s13, s7, s3
	s_cselect_b32 s53, s6, s2
	s_add_u32 s54, s2, 0x100
	v_mov_b32_e32 v12, 0
	s_addc_u32 s55, s3, 0
	s_mov_b32 s56, -2
	s_mov_b64 s[2:3], 0
	v_add_u32_e32 v168, 0x10000, v3
	v_add_u32_e32 v169, 0x14000, v3
	v_add_u32_e32 v170, 0x18000, v3
	v_add_u32_e32 v171, 0x1c000, v3
	s_cmp_lg_u64 s[10:11], 0
	s_cbranch_scc1 .Lprio_P4
	s_setprio 1
.Lprio_P4:
	s_add_u32 s36, s31, s2
	s_addc_u32 s37, s91, s3
	s_add_u32 s36, s36, 0x16200100
	s_addc_u32 s37, s37, 0
	s_add_u32 s57, s54, s2
	s_addc_u32 s58, s55, s3
	s_add_i32 s59, 0, 0x10000
	s_cmpk_eq_i32 s2, 0xf00
	s_cselect_b32 s41, s1, s37
	s_cselect_b32 s40, s0, s36
	s_cselect_b32 s37, s13, s58
	s_cselect_b32 s36, s53, s57
	s_add_i32 s57, 0, 0x14000
	ds_read_b128 v[142:145], v168
	ds_read_b128 v[152:155], v168 offset:1024
	ds_read_b128 v[156:159], v168 offset:2048
	ds_read_b128 v[172:175], v168 offset:3072
	ds_read_b128 v[176:179], v169
	ds_read_b128 v[180:183], v169 offset:1024
	ds_read_b128 v[184:187], v169 offset:2048
	ds_read_b128 v[188:191], v169 offset:3072
	v_lshl_add_u64 v[146:147], v[138:139], 0, s[2:3]
	s_add_i32 m0, s43, 0xc000
	ds_read_b128 v[192:195], v150
	ds_read_b128 v[196:199], v150 offset:1024
	ds_read_b128 v[200:203], v150 offset:2048
	ds_read_b128 v[212:215], v150 offset:3072
	ds_read_b128 v[216:219], v150 offset:4096
	ds_read_b128 v[220:223], v150 offset:5120
	ds_read_b128 v[224:227], v150 offset:6144
	ds_read_b128 v[228:231], v150 offset:7168
	global_load_lds_dwordx4 v[146:147], off
	v_lshl_add_u64 v[146:147], v[140:141], 0, s[2:3]
	s_add_i32 m0, s43, 0xe000
	s_nop 0
	global_load_lds_dwordx4 v[146:147], off
	s_waitcnt vmcnt(8)
	s_waitcnt lgkmcnt(0)
	s_barrier
	s_waitcnt lgkmcnt(0)
	v_mfma_f32_16x16x32_bf16 v[120:123], v[142:145], v[192:195], 0
	v_mfma_f32_16x16x32_bf16 v[116:119], v[156:159], v[192:195], 0
	v_mfma_f32_16x16x32_bf16 v[104:107], v[142:145], v[200:203], 0
	v_mfma_f32_16x16x32_bf16 v[100:103], v[156:159], v[200:203], 0
	v_mfma_f32_16x16x32_bf16 v[88:91], v[142:145], v[216:219], 0
	v_mfma_f32_16x16x32_bf16 v[84:87], v[156:159], v[216:219], 0
	v_mfma_f32_16x16x32_bf16 v[72:75], v[142:145], v[224:227], 0
	v_mfma_f32_16x16x32_bf16 v[68:71], v[156:159], v[224:227], 0
	v_mfma_f32_16x16x32_bf16 v[120:123], v[152:155], v[196:199], v[120:123]
	v_mfma_f32_16x16x32_bf16 v[116:119], v[172:175], v[196:199], v[116:119]
	v_mfma_f32_16x16x32_bf16 v[104:107], v[152:155], v[212:215], v[104:107]
	v_mfma_f32_16x16x32_bf16 v[100:103], v[172:175], v[212:215], v[100:103]
	v_mfma_f32_16x16x32_bf16 v[88:91], v[152:155], v[220:223], v[88:91]
	v_mfma_f32_16x16x32_bf16 v[84:87], v[172:175], v[220:223], v[84:87]
	v_mfma_f32_16x16x32_bf16 v[72:75], v[152:155], v[228:231], v[72:75]
	v_mfma_f32_16x16x32_bf16 v[68:71], v[172:175], v[228:231], v[68:71]
	v_mfma_f32_16x16x32_bf16 v[128:131], v[176:179], v[192:195], 0
	v_mfma_f32_16x16x32_bf16 v[124:127], v[184:187], v[192:195], 0
	v_mfma_f32_16x16x32_bf16 v[112:115], v[176:179], v[200:203], 0
	v_mfma_f32_16x16x32_bf16 v[108:111], v[184:187], v[200:203], 0
	v_mfma_f32_16x16x32_bf16 v[96:99], v[176:179], v[216:219], 0
	v_mfma_f32_16x16x32_bf16 v[92:95], v[184:187], v[216:219], 0
	v_mfma_f32_16x16x32_bf16 v[80:83], v[176:179], v[224:227], 0
	v_mfma_f32_16x16x32_bf16 v[76:79], v[184:187], v[224:227], 0
	v_mfma_f32_16x16x32_bf16 v[128:131], v[180:183], v[196:199], v[128:131]
	v_mfma_f32_16x16x32_bf16 v[124:127], v[188:191], v[196:199], v[124:127]
	v_mfma_f32_16x16x32_bf16 v[112:115], v[180:183], v[212:215], v[112:115]
	v_mfma_f32_16x16x32_bf16 v[108:111], v[188:191], v[212:215], v[108:111]
	v_mfma_f32_16x16x32_bf16 v[96:99], v[180:183], v[220:223], v[96:99]
	v_mfma_f32_16x16x32_bf16 v[92:95], v[188:191], v[220:223], v[92:95]
	v_mfma_f32_16x16x32_bf16 v[80:83], v[180:183], v[228:231], v[80:83]
	v_mfma_f32_16x16x32_bf16 v[76:79], v[188:191], v[228:231], v[76:79]
	s_barrier
	s_add_i32 s58, s59, s42
	s_add_u32 s98, s36, 0x80
	s_addc_u32 s99, s37, 0
	s_mov_b32 m0, s58
	ds_read_b128 v[192:195], v150 offset:16384
	ds_read_b128 v[196:199], v150 offset:17408
	ds_read_b128 v[200:203], v150 offset:18432
	ds_read_b128 v[212:215], v150 offset:19456
	ds_read_b128 v[216:219], v150 offset:20480
	ds_read_b128 v[220:223], v150 offset:21504
	ds_read_b128 v[224:227], v150 offset:22528
	ds_read_b128 v[228:231], v150 offset:23552
	global_load_lds_dwordx4 v134, s[36:37]
	s_add_i32 m0, s58, 0x2000
	s_add_u32 s58, s36, 0x80000
	s_addc_u32 s59, s37, 0
	s_add_i32 s57, s57, s42
	global_load_lds_dwordx4 v0, s[36:37]
	s_mov_b32 m0, s57
	s_add_u32 s100, s40, 0x80
	s_addc_u32 s101, s41, 0
	s_nop 0
	global_load_lds_dwordx4 v134, s[58:59]
	s_add_i32 m0, s57, 0x2000
	s_nop 0
	global_load_lds_dwordx4 v0, s[58:59]
	s_mov_b32 m0, s43
	s_nop 0
	global_load_lds_dwordx4 v136, s[40:41]
	s_mov_b32 m0, s44
	s_nop 0
	global_load_lds_dwordx4 v132, s[40:41]
	s_waitcnt vmcnt(8)
	s_waitcnt lgkmcnt(0)
	s_barrier
; #define PG8_STAGE(bufoff, gbase, voff) do { _Pragma("unroll") for (int _i = 0; _i < 2; ++_i) \
;         __builtin_amdgcn_global_load_lds((const unsigned*)((const char*)(gbase) + (voff)[_i]), (PG8_LAS unsigned*)(lds + (bufoff) + ldsw + _i * 8192), 16, 0, 0); } while (0)
; #define PG8_LDA(dst, b, h) do { _Pragma("unroll") for (int m = 0; m < 4; ++m) _Pragma("unroll") for (int k = 0; k < 2; ++k) dst[m][k] = *(const PG8_LAS bf16x8*)(lds + PG8_SA(b, h) + aoff + m * 2048 + k * 1024); } while (0)
; #define PG8_LDB(dst, b, h) do { _Pragma("unroll") for (int n = 0; n < 2; ++n) _Pragma("unroll") for (int k = 0; k < 2; ++k) dst[n][k] = *(const PG8_LAS bf16x8*)(lds + PG8_SB(b, h) + boff + n * 2048 + k * 1024); } while (0)
; #define PG8_MMA(ai, bj, At, Bt) do { __builtin_amdgcn_s_setprio(1); _Pragma("unroll") for (int m = 0; m < 4; ++m) _Pragma("unroll") for (int n = 0; n < 2; ++n) _Pragma("unroll") for (int k = 0; k < 2; ++k) \
;         acc[ai][bj][m][n] = __builtin_amdgcn_mfma_f32_16x16x32_bf16(Bt[n][k], At[m][k], acc[ai][bj][m][n], 0, 0, 0); __builtin_amdgcn_s_setprio(0); } while (0)
; #define PG8_WAIT_V(n) asm volatile("s_waitcnt vmcnt(" #n ")" ::: "memory")
; #define PG8_WAIT_L(n) asm volatile("s_waitcnt lgkmcnt(" #n ")" ::: "memory")
; #define PG8_BAR __builtin_amdgcn_s_barrier()
; #define PG8_SCHED __builtin_amdgcn_sched_barrier(0)
; template <class Epi, class Sched, bool ALIGN_EPI = false, bool SP2 = false>
; __device__ __forceinline__ void gemm_phase(PG8_LAS unsigned char* lds, const Gemm g, const Sched& S, const Epi& E) {
;     ...
;             PG8_WAIT_V(8); PG8_WAIT_L(0); PG8_BAR; PG8_MMA(0, 0, At, B0); PG8_MMA(0, 1, At, B1); PG8_BAR; PG8_SCHED;
;             PG8_LDA(At, 0, 1); PG8_STAGE(PG8_SB(0, 0), b2, voffB); PG8_STAGE(PG8_SB(0, 1), b2 + hstep, voffB); PG8_STAGE(PG8_SA(0, 0), a2, voffA);
;             PG8_WAIT_V(8); PG8_WAIT_L(0); PG8_BAR; PG8_MMA(1, 0, At, B0); PG8_MMA(1, 1, At, B1); PG8_BAR; PG8_SCHED;
;             PG8_LDB(B0, 1, 0); PG8_LDB(B1, 1, 1); PG8_SCHED; PG8_LDA(At, 1, 0); PG8_STAGE(PG8_SA(0, 1), a2 + hstep, voffA);
;             PG8_WAIT_V(8); PG8_WAIT_L(0); PG8_BAR; PG8_MMA(0, 0, At, B0); PG8_MMA(0, 1, At, B1); PG8_BAR; PG8_SCHED;
	s_waitcnt lgkmcnt(0)
	v_mfma_f32_16x16x32_bf16 v[56:59], v[142:145], v[192:195], 0
	v_mfma_f32_16x16x32_bf16 v[52:55], v[156:159], v[192:195], 0
	v_mfma_f32_16x16x32_bf16 v[40:43], v[142:145], v[200:203], 0
	v_mfma_f32_16x16x32_bf16 v[36:39], v[156:159], v[200:203], 0
	v_mfma_f32_16x16x32_bf16 v[24:27], v[142:145], v[216:219], 0
	v_mfma_f32_16x16x32_bf16 v[20:23], v[156:159], v[216:219], 0
	v_mfma_f32_16x16x32_bf16 v[8:11], v[142:145], v[224:227], 0
	v_mfma_f32_16x16x32_bf16 v[4:7], v[156:159], v[224:227], 0
	v_mfma_f32_16x16x32_bf16 v[56:59], v[152:155], v[196:199], v[56:59]
	v_mfma_f32_16x16x32_bf16 v[52:55], v[172:175], v[196:199], v[52:55]
	v_mfma_f32_16x16x32_bf16 v[40:43], v[152:155], v[212:215], v[40:43]
	v_mfma_f32_16x16x32_bf16 v[36:39], v[172:175], v[212:215], v[36:39]
	v_mfma_f32_16x16x32_bf16 v[24:27], v[152:155], v[220:223], v[24:27]
	v_mfma_f32_16x16x32_bf16 v[20:23], v[172:175], v[220:223], v[20:23]
	v_mfma_f32_16x16x32_bf16 v[8:11], v[152:155], v[228:231], v[8:11]
	v_mfma_f32_16x16x32_bf16 v[4:7], v[172:175], v[228:231], v[4:7]
	v_mfma_f32_16x16x32_bf16 v[64:67], v[176:179], v[192:195], 0
	v_mfma_f32_16x16x32_bf16 v[60:63], v[184:187], v[192:195], 0
	v_mfma_f32_16x16x32_bf16 v[48:51], v[176:179], v[200:203], 0
	v_mfma_f32_16x16x32_bf16 v[44:47], v[184:187], v[200:203], 0
	v_mfma_f32_16x16x32_bf16 v[32:35], v[176:179], v[216:219], 0
	v_mfma_f32_16x16x32_bf16 v[28:31], v[184:187], v[216:219], 0
	v_mfma_f32_16x16x32_bf16 v[16:19], v[176:179], v[224:227], 0
	v_mfma_f32_16x16x32_bf16 v[12:15], v[184:187], v[224:227], 0
	v_mfma_f32_16x16x32_bf16 v[64:67], v[180:183], v[196:199], v[64:67]
	v_mfma_f32_16x16x32_bf16 v[60:63], v[188:191], v[196:199], v[60:63]
	v_mfma_f32_16x16x32_bf16 v[48:51], v[180:183], v[212:215], v[48:51]
	v_mfma_f32_16x16x32_bf16 v[44:47], v[188:191], v[212:215], v[44:47]
	v_mfma_f32_16x16x32_bf16 v[32:35], v[180:183], v[220:223], v[32:35]
	v_mfma_f32_16x16x32_bf16 v[28:31], v[188:191], v[220:223], v[28:31]
	v_mfma_f32_16x16x32_bf16 v[16:19], v[180:183], v[228:231], v[16:19]
	v_mfma_f32_16x16x32_bf16 v[12:15], v[188:191], v[228:231], v[12:15]
	s_barrier
	s_add_i32 s57, 0, 0x18000
	s_add_i32 s58, 0, 0x1c000
	ds_read_b128 v[142:145], v170
	ds_read_b128 v[152:155], v170 offset:1024
	ds_read_b128 v[156:159], v170 offset:2048
	ds_read_b128 v[172:175], v170 offset:3072
	ds_read_b128 v[176:179], v171
	ds_read_b128 v[180:183], v171 offset:1024
	ds_read_b128 v[184:187], v171 offset:2048
	ds_read_b128 v[188:191], v171 offset:3072
	s_add_u32 s40, s40, 0x80000
	s_addc_u32 s41, s41, 0
	s_mov_b32 m0, s45
	ds_read_b128 v[192:195], v150 offset:32768
	ds_read_b128 v[196:199], v150 offset:33792
	ds_read_b128 v[200:203], v150 offset:34816
	ds_read_b128 v[212:215], v150 offset:35840
	ds_read_b128 v[216:219], v150 offset:36864
	ds_read_b128 v[220:223], v150 offset:37888
	ds_read_b128 v[224:227], v150 offset:38912
	ds_read_b128 v[228:231], v150 offset:39936
	global_load_lds_dwordx4 v136, s[40:41]
	s_mov_b32 m0, s48
	s_nop 0
	global_load_lds_dwordx4 v132, s[40:41]
	s_waitcnt vmcnt(8)
	s_waitcnt lgkmcnt(0)
	s_barrier
	s_waitcnt lgkmcnt(0)
	v_mfma_f32_16x16x32_bf16 v[120:123], v[142:145], v[192:195], v[120:123]
	v_mfma_f32_16x16x32_bf16 v[116:119], v[156:159], v[192:195], v[116:119]
	v_mfma_f32_16x16x32_bf16 v[104:107], v[142:145], v[200:203], v[104:107]
	v_mfma_f32_16x16x32_bf16 v[100:103], v[156:159], v[200:203], v[100:103]
	v_mfma_f32_16x16x32_bf16 v[88:91], v[142:145], v[216:219], v[88:91]
	v_mfma_f32_16x16x32_bf16 v[84:87], v[156:159], v[216:219], v[84:87]
	v_mfma_f32_16x16x32_bf16 v[72:75], v[142:145], v[224:227], v[72:75]
	v_mfma_f32_16x16x32_bf16 v[68:71], v[156:159], v[224:227], v[68:71]
	v_mfma_f32_16x16x32_bf16 v[120:123], v[152:155], v[196:199], v[120:123]
	v_mfma_f32_16x16x32_bf16 v[116:119], v[172:175], v[196:199], v[116:119]
	v_mfma_f32_16x16x32_bf16 v[104:107], v[152:155], v[212:215], v[104:107]
	v_mfma_f32_16x16x32_bf16 v[100:103], v[172:175], v[212:215], v[100:103]
	v_mfma_f32_16x16x32_bf16 v[88:91], v[152:155], v[220:223], v[88:91]
	v_mfma_f32_16x16x32_bf16 v[84:87], v[172:175], v[220:223], v[84:87]
	v_mfma_f32_16x16x32_bf16 v[72:75], v[152:155], v[228:231], v[72:75]
	v_mfma_f32_16x16x32_bf16 v[68:71], v[172:175], v[228:231], v[68:71]
	v_mfma_f32_16x16x32_bf16 v[128:131], v[176:179], v[192:195], v[128:131]
	v_mfma_f32_16x16x32_bf16 v[124:127], v[184:187], v[192:195], v[124:127]
	v_mfma_f32_16x16x32_bf16 v[112:115], v[176:179], v[200:203], v[112:115]
	v_mfma_f32_16x16x32_bf16 v[108:111], v[184:187], v[200:203], v[108:111]
	v_mfma_f32_16x16x32_bf16 v[96:99], v[176:179], v[216:219], v[96:99]
	v_mfma_f32_16x16x32_bf16 v[92:95], v[184:187], v[216:219], v[92:95]
	v_mfma_f32_16x16x32_bf16 v[80:83], v[176:179], v[224:227], v[80:83]
	v_mfma_f32_16x16x32_bf16 v[76:79], v[184:187], v[224:227], v[76:79]
	v_mfma_f32_16x16x32_bf16 v[128:131], v[180:183], v[196:199], v[128:131]
	v_mfma_f32_16x16x32_bf16 v[124:127], v[188:191], v[196:199], v[124:127]
	v_mfma_f32_16x16x32_bf16 v[112:115], v[180:183], v[212:215], v[112:115]
	v_mfma_f32_16x16x32_bf16 v[108:111], v[188:191], v[212:215], v[108:111]
	v_mfma_f32_16x16x32_bf16 v[96:99], v[180:183], v[220:223], v[96:99]
	v_mfma_f32_16x16x32_bf16 v[92:95], v[188:191], v[220:223], v[92:95]
	v_mfma_f32_16x16x32_bf16 v[80:83], v[180:183], v[228:231], v[80:83]
	v_mfma_f32_16x16x32_bf16 v[76:79], v[188:191], v[228:231], v[76:79]
	s_barrier
; #define PG8_STAGE(bufoff, gbase, voff) do { _Pragma("unroll") for (int _i = 0; _i < 2; ++_i) \
;         __builtin_amdgcn_global_load_lds((const unsigned*)((const char*)(gbase) + (voff)[_i]), (PG8_LAS unsigned*)(lds + (bufoff) + ldsw + _i * 8192), 16, 0, 0); } while (0)
; #define PG8_LDA(dst, b, h) do { _Pragma("unroll") for (int m = 0; m < 4; ++m) _Pragma("unroll") for (int k = 0; k < 2; ++k) dst[m][k] = *(const PG8_LAS bf16x8*)(lds + PG8_SA(b, h) + aoff + m * 2048 + k * 1024); } while (0)
; #define PG8_MMA(ai, bj, At, Bt) do { __builtin_amdgcn_s_setprio(1); _Pragma("unroll") for (int m = 0; m < 4; ++m) _Pragma("unroll") for (int n = 0; n < 2; ++n) _Pragma("unroll") for (int k = 0; k < 2; ++k) \
;         acc[ai][bj][m][n] = __builtin_amdgcn_mfma_f32_16x16x32_bf16(Bt[n][k], At[m][k], acc[ai][bj][m][n], 0, 0, 0); __builtin_amdgcn_s_setprio(0); } while (0)
; #define PG8_WAIT_V(n) asm volatile("s_waitcnt vmcnt(" #n ")" ::: "memory")
; #define PG8_WAIT_L(n) asm volatile("s_waitcnt lgkmcnt(" #n ")" ::: "memory")
; #define PG8_BAR __builtin_amdgcn_s_barrier()
; #define PG8_SCHED __builtin_amdgcn_sched_barrier(0)
; template <class Epi, class Sched, bool ALIGN_EPI = false, bool SP2 = false>
; __device__ __forceinline__ void gemm_phase(PG8_LAS unsigned char* lds, const Gemm g, const Sched& S, const Epi& E) {
;     ...
;             PG8_LDA(At, 1, 1); PG8_STAGE(PG8_SB(1, 0), b3, voffB); PG8_STAGE(PG8_SB(1, 1), b3 + hstep, voffB); PG8_STAGE(PG8_SA(1, 0), a3, voffA);
;             PG8_WAIT_V(8); PG8_WAIT_L(0); PG8_BAR; PG8_MMA(1, 0, At, B0); PG8_MMA(1, 1, At, B1); PG8_BAR; PG8_SCHED;
	s_add_i32 s40, s57, s42
	s_mov_b32 m0, s40
	ds_read_b128 v[192:195], v150 offset:49152
	ds_read_b128 v[196:199], v150 offset:50176
	ds_read_b128 v[200:203], v150 offset:51200
	ds_read_b128 v[212:215], v150 offset:52224
	ds_read_b128 v[216:219], v150 offset:53248
	ds_read_b128 v[220:223], v150 offset:54272
	ds_read_b128 v[224:227], v150 offset:55296
	ds_read_b128 v[228:231], v150 offset:56320
	global_load_lds_dwordx4 v134, s[98:99]
	s_add_i32 m0, s40, 0x2000
	s_add_u32 s36, s36, 0x80080
	s_addc_u32 s37, s37, 0
	s_add_i32 s40, s58, s42
	global_load_lds_dwordx4 v0, s[98:99]
	s_mov_b32 m0, s40
	s_nop 0
	global_load_lds_dwordx4 v134, s[36:37]
	s_add_i32 m0, s40, 0x2000
	s_nop 0
	global_load_lds_dwordx4 v0, s[36:37]
	s_mov_b32 m0, s49
	s_nop 0
	global_load_lds_dwordx4 v136, s[100:101]
	s_mov_b32 m0, s50
	s_nop 0
	global_load_lds_dwordx4 v132, s[100:101]
	s_waitcnt vmcnt(8)
	s_waitcnt lgkmcnt(0)
	s_barrier
	s_waitcnt lgkmcnt(0)
	v_mfma_f32_16x16x32_bf16 v[56:59], v[142:145], v[192:195], v[56:59]
	v_mfma_f32_16x16x32_bf16 v[52:55], v[156:159], v[192:195], v[52:55]
	v_mfma_f32_16x16x32_bf16 v[40:43], v[142:145], v[200:203], v[40:43]
	v_mfma_f32_16x16x32_bf16 v[36:39], v[156:159], v[200:203], v[36:39]
	v_mfma_f32_16x16x32_bf16 v[24:27], v[142:145], v[216:219], v[24:27]
	v_mfma_f32_16x16x32_bf16 v[20:23], v[156:159], v[216:219], v[20:23]
	v_mfma_f32_16x16x32_bf16 v[8:11], v[142:145], v[224:227], v[8:11]
	v_mfma_f32_16x16x32_bf16 v[4:7], v[156:159], v[224:227], v[4:7]
	v_mfma_f32_16x16x32_bf16 v[56:59], v[152:155], v[196:199], v[56:59]
	v_mfma_f32_16x16x32_bf16 v[52:55], v[172:175], v[196:199], v[52:55]
	v_mfma_f32_16x16x32_bf16 v[40:43], v[152:155], v[212:215], v[40:43]
	v_mfma_f32_16x16x32_bf16 v[36:39], v[172:175], v[212:215], v[36:39]
	v_mfma_f32_16x16x32_bf16 v[24:27], v[152:155], v[220:223], v[24:27]
	v_mfma_f32_16x16x32_bf16 v[20:23], v[172:175], v[220:223], v[20:23]
	v_mfma_f32_16x16x32_bf16 v[8:11], v[152:155], v[228:231], v[8:11]
	v_mfma_f32_16x16x32_bf16 v[4:7], v[172:175], v[228:231], v[4:7]
	v_mfma_f32_16x16x32_bf16 v[64:67], v[176:179], v[192:195], v[64:67]
	v_mfma_f32_16x16x32_bf16 v[60:63], v[184:187], v[192:195], v[60:63]
	v_mfma_f32_16x16x32_bf16 v[48:51], v[176:179], v[200:203], v[48:51]
	v_mfma_f32_16x16x32_bf16 v[44:47], v[184:187], v[200:203], v[44:47]
	v_mfma_f32_16x16x32_bf16 v[32:35], v[176:179], v[216:219], v[32:35]
	v_mfma_f32_16x16x32_bf16 v[28:31], v[184:187], v[216:219], v[28:31]
	v_mfma_f32_16x16x32_bf16 v[16:19], v[176:179], v[224:227], v[16:19]
	v_mfma_f32_16x16x32_bf16 v[12:15], v[184:187], v[224:227], v[12:15]
	v_mfma_f32_16x16x32_bf16 v[64:67], v[180:183], v[196:199], v[64:67]
	v_mfma_f32_16x16x32_bf16 v[60:63], v[188:191], v[196:199], v[60:63]
	v_mfma_f32_16x16x32_bf16 v[48:51], v[180:183], v[212:215], v[48:51]
	v_mfma_f32_16x16x32_bf16 v[44:47], v[188:191], v[212:215], v[44:47]
	v_mfma_f32_16x16x32_bf16 v[32:35], v[180:183], v[220:223], v[32:35]
	v_mfma_f32_16x16x32_bf16 v[28:31], v[188:191], v[220:223], v[28:31]
	v_mfma_f32_16x16x32_bf16 v[16:19], v[180:183], v[228:231], v[16:19]
	v_mfma_f32_16x16x32_bf16 v[12:15], v[188:191], v[228:231], v[12:15]
	s_barrier
	s_add_i32 s56, s56, 2
	s_add_u32 s2, s2, 0x100
	s_addc_u32 s3, s3, 0
	s_cmp_gt_u32 s56, 29

; #define PG8_STAGE(bufoff, gbase, voff) do { _Pragma("unroll") for (int _i = 0; _i < 2; ++_i) \
;         __builtin_amdgcn_global_load_lds((const unsigned*)((const char*)(gbase) + (voff)[_i]), (PG8_LAS unsigned*)(lds + (bufoff) + ldsw + _i * 8192), 16, 0, 0); } while (0)
; #define PG8_LDA(dst, b, h) do { _Pragma("unroll") for (int m = 0; m < 4; ++m) _Pragma("unroll") for (int k = 0; k < 2; ++k) dst[m][k] = *(const PG8_LAS bf16x8*)(lds + PG8_SA(b, h) + aoff + m * 2048 + k * 1024); } while (0)
; #define PG8_LDB(dst, b, h) do { _Pragma("unroll") for (int n = 0; n < 2; ++n) _Pragma("unroll") for (int k = 0; k < 2; ++k) dst[n][k] = *(const PG8_LAS bf16x8*)(lds + PG8_SB(b, h) + boff + n * 2048 + k * 1024); } while (0)
; #define PG8_MMA(ai, bj, At, Bt) do { __builtin_amdgcn_s_setprio(1); _Pragma("unroll") for (int m = 0; m < 4; ++m) _Pragma("unroll") for (int n = 0; n < 2; ++n) _Pragma("unroll") for (int k = 0; k < 2; ++k) \
;         acc[ai][bj][m][n] = __builtin_amdgcn_mfma_f32_16x16x32_bf16(Bt[n][k], At[m][k], acc[ai][bj][m][n], 0, 0, 0); __builtin_amdgcn_s_setprio(0); } while (0)
; #define PG8_WAIT_V(n) asm volatile("s_waitcnt vmcnt(" #n ")" ::: "memory")
; template <class Epi, class Sched, bool ALIGN_EPI = false, bool SP2 = false>
; __device__ __forceinline__ void gemm_phase(PG8_LAS unsigned char* lds, const Gemm g, const Sched& S, const Epi& E) {
;     ...
;         const bool has_next = S.next(ui + 1, nxt);
;         const char* nA = has_next ? (const char*)g.A + (size_t)nxt.pm * tstep : cA; const char* nB = has_next ? (const char*)g.Bt + (size_t)nxt.pn * tstep : cB;
;         for (int t = 0; t < nt; t += 2) {
;             const bool last = (t == nt - 2);
;             const char* a1 = cA + (size_t)(t + 1) * kstep;
;             const char* a2 = last ? nA : cA + (size_t)(t + 2) * kstep; const char* b2 = last ? nB : cB + (size_t)(t + 2) * kstep;
;             const char* a3 = a2 + kstep; const char* b3 = b2 + kstep;
;             if (last && has_next) S.a_ready(nxt);
;             if constexpr (Epi::KSPLIT) { if (t == (nt >> 1)) E.mid(acc, cur, wr, wc, fr, fq); }
;             if constexpr (SP2) {
;             PG8_LDB(B0, 0, 0); PG8_LDB(B1, 0, 1); PG8_SCHED; PG8_LDA(At, 0, 0); PG8_STAGE(PG8_SA(1, 1), a1 + hstep, voffA);
;             PG8_WAIT_V(8); PG8_WAIT_L(0); PG8_BAR; PG8_MMA(0, 0, At, B0); PG8_MMA(0, 1, At, B1); PG8_BAR; PG8_SCHED;
.LBB0_1277:
	s_add_u32 s61, s2, 0x100
	v_mov_b32_e32 v4, 0
	s_addc_u32 s66, s3, 0
	s_mov_b32 s67, -2
	s_mov_b64 s[2:3], 0
	s_waitcnt lgkmcnt(0)
	v_add_u32_e32 v168, 0x10000, v3
	v_add_u32_e32 v169, 0x14000, v3
	v_add_u32_e32 v170, 0x18000, v3
	v_add_u32_e32 v171, 0x1c000, v3
	s_cmp_lg_u64 s[12:13], 0
	s_cbranch_scc1 .Lprio_P5
	s_setprio 1
.Lprio_P5:
	s_add_u32 s38, s93, s2
	s_addc_u32 s39, s95, s3
	s_add_u32 s38, s38, 0x1da00100
	s_addc_u32 s39, s39, 0
	s_add_u32 s68, s61, s2
	s_addc_u32 s69, s66, s3
	s_add_i32 s70, 0, 0x10000
	s_cmpk_eq_i32 s2, 0x2b00
	s_cselect_b32 s47, s35, s39
	s_cselect_b32 s46, s34, s38
	s_cselect_b32 s39, s43, s69
	s_cselect_b32 s38, s42, s68
	s_add_i32 s71, 0, 0x14000
	ds_read_b128 v[124:127], v168
	ds_read_b128 v[136:139], v168 offset:1024
	ds_read_b128 v[140:143], v168 offset:2048
	ds_read_b128 v[144:147], v168 offset:3072
	ds_read_b128 v[148:151], v169
	ds_read_b128 v[152:155], v169 offset:1024
	ds_read_b128 v[156:159], v169 offset:2048
	ds_read_b128 v[182:185], v169 offset:3072
	v_lshl_add_u64 v[202:203], v[178:179], 0, s[2:3]
	s_add_i32 m0, s49, 0xc000
	ds_read_b128 v[186:189], v214
	ds_read_b128 v[190:193], v214 offset:1024
	ds_read_b128 v[194:197], v214 offset:2048
	ds_read_b128 v[198:201], v214 offset:3072
	ds_read_b128 v[216:219], v214 offset:4096
	ds_read_b128 v[220:223], v214 offset:5120
	ds_read_b128 v[224:227], v214 offset:6144
	ds_read_b128 v[228:231], v214 offset:7168
	global_load_lds_dwordx4 v[202:203], off
	v_lshl_add_u64 v[202:203], v[180:181], 0, s[2:3]
	s_add_i32 m0, s49, 0xe000
	s_nop 0
	global_load_lds_dwordx4 v[202:203], off
	s_waitcnt vmcnt(8)
	s_waitcnt lgkmcnt(0)
	s_barrier
	s_waitcnt lgkmcnt(0)
	v_mfma_f32_16x16x32_bf16 v[132:135], v[124:127], v[186:189], 0
	v_mfma_f32_16x16x32_bf16 v[128:131], v[140:143], v[186:189], 0
	v_mfma_f32_16x16x32_bf16 v[112:115], v[124:127], v[194:197], 0
	v_mfma_f32_16x16x32_bf16 v[108:111], v[140:143], v[194:197], 0
	v_mfma_f32_16x16x32_bf16 v[96:99], v[124:127], v[216:219], 0
	v_mfma_f32_16x16x32_bf16 v[92:95], v[140:143], v[216:219], 0
	v_mfma_f32_16x16x32_bf16 v[80:83], v[124:127], v[224:227], 0
	v_mfma_f32_16x16x32_bf16 v[76:79], v[140:143], v[224:227], 0
	v_mfma_f32_16x16x32_bf16 v[132:135], v[136:139], v[190:193], v[132:135]
	v_mfma_f32_16x16x32_bf16 v[128:131], v[144:147], v[190:193], v[128:131]
	v_mfma_f32_16x16x32_bf16 v[112:115], v[136:139], v[198:201], v[112:115]
	v_mfma_f32_16x16x32_bf16 v[108:111], v[144:147], v[198:201], v[108:111]
	v_mfma_f32_16x16x32_bf16 v[96:99], v[136:139], v[220:223], v[96:99]
	v_mfma_f32_16x16x32_bf16 v[92:95], v[144:147], v[220:223], v[92:95]
	v_mfma_f32_16x16x32_bf16 v[80:83], v[136:139], v[228:231], v[80:83]
	v_mfma_f32_16x16x32_bf16 v[76:79], v[144:147], v[228:231], v[76:79]
	v_mfma_f32_16x16x32_bf16 v[120:123], v[148:151], v[186:189], 0
	v_mfma_f32_16x16x32_bf16 v[116:119], v[156:159], v[186:189], 0
	v_mfma_f32_16x16x32_bf16 v[104:107], v[148:151], v[194:197], 0
	v_mfma_f32_16x16x32_bf16 v[100:103], v[156:159], v[194:197], 0
	v_mfma_f32_16x16x32_bf16 v[88:91], v[148:151], v[216:219], 0
	v_mfma_f32_16x16x32_bf16 v[84:87], v[156:159], v[216:219], 0
	v_mfma_f32_16x16x32_bf16 v[72:75], v[148:151], v[224:227], 0
	v_mfma_f32_16x16x32_bf16 v[68:71], v[156:159], v[224:227], 0
	v_mfma_f32_16x16x32_bf16 v[120:123], v[152:155], v[190:193], v[120:123]
	v_mfma_f32_16x16x32_bf16 v[116:119], v[182:185], v[190:193], v[116:119]
	v_mfma_f32_16x16x32_bf16 v[104:107], v[152:155], v[198:201], v[104:107]
	v_mfma_f32_16x16x32_bf16 v[100:103], v[182:185], v[198:201], v[100:103]
	v_mfma_f32_16x16x32_bf16 v[88:91], v[152:155], v[220:223], v[88:91]
	v_mfma_f32_16x16x32_bf16 v[84:87], v[182:185], v[220:223], v[84:87]
	v_mfma_f32_16x16x32_bf16 v[72:75], v[152:155], v[228:231], v[72:75]
	v_mfma_f32_16x16x32_bf16 v[68:71], v[182:185], v[228:231], v[68:71]
	s_barrier
	s_add_i32 s68, s70, s48
	s_add_u32 s98, s38, 0x80
	s_addc_u32 s99, s39, 0
	s_mov_b32 m0, s68
	ds_read_b128 v[186:189], v214 offset:16384
	ds_read_b128 v[190:193], v214 offset:17408
	ds_read_b128 v[194:197], v214 offset:18432
	ds_read_b128 v[198:201], v214 offset:19456
	ds_read_b128 v[216:219], v214 offset:20480
	ds_read_b128 v[220:223], v214 offset:21504
	ds_read_b128 v[224:227], v214 offset:22528
	ds_read_b128 v[228:231], v214 offset:23552
	global_load_lds_dwordx4 v174, s[38:39]
	s_add_i32 m0, s68, 0x2000
	s_add_u32 s68, s38, 0x160000
	s_addc_u32 s69, s39, 0
	s_add_i32 s70, s71, s48
	global_load_lds_dwordx4 v0, s[38:39]
	s_mov_b32 m0, s70
	s_add_u32 s100, s46, 0x80
	s_addc_u32 s101, s47, 0
	s_nop 0
	global_load_lds_dwordx4 v174, s[68:69]
	s_add_i32 m0, s70, 0x2000
	s_nop 0
	global_load_lds_dwordx4 v0, s[68:69]
	s_mov_b32 m0, s49
	s_nop 0
	global_load_lds_dwordx4 v176, s[46:47]
	s_mov_b32 m0, s50
	s_nop 0
	global_load_lds_dwordx4 v172, s[46:47]
	s_waitcnt vmcnt(8)
	s_waitcnt lgkmcnt(0)
	s_barrier
; #define PG8_STAGE(bufoff, gbase, voff) do { _Pragma("unroll") for (int _i = 0; _i < 2; ++_i) \
;         __builtin_amdgcn_global_load_lds((const unsigned*)((const char*)(gbase) + (voff)[_i]), (PG8_LAS unsigned*)(lds + (bufoff) + ldsw + _i * 8192), 16, 0, 0); } while (0)
; #define PG8_LDA(dst, b, h) do { _Pragma("unroll") for (int m = 0; m < 4; ++m) _Pragma("unroll") for (int k = 0; k < 2; ++k) dst[m][k] = *(const PG8_LAS bf16x8*)(lds + PG8_SA(b, h) + aoff + m * 2048 + k * 1024); } while (0)
; #define PG8_LDB(dst, b, h) do { _Pragma("unroll") for (int n = 0; n < 2; ++n) _Pragma("unroll") for (int k = 0; k < 2; ++k) dst[n][k] = *(const PG8_LAS bf16x8*)(lds + PG8_SB(b, h) + boff + n * 2048 + k * 1024); } while (0)
; #define PG8_MMA(ai, bj, At, Bt) do { __builtin_amdgcn_s_setprio(1); _Pragma("unroll") for (int m = 0; m < 4; ++m) _Pragma("unroll") for (int n = 0; n < 2; ++n) _Pragma("unroll") for (int k = 0; k < 2; ++k) \
;         acc[ai][bj][m][n] = __builtin_amdgcn_mfma_f32_16x16x32_bf16(Bt[n][k], At[m][k], acc[ai][bj][m][n], 0, 0, 0); __builtin_amdgcn_s_setprio(0); } while (0)
; #define PG8_WAIT_V(n) asm volatile("s_waitcnt vmcnt(" #n ")" ::: "memory")
; #define PG8_WAIT_L(n) asm volatile("s_waitcnt lgkmcnt(" #n ")" ::: "memory")
; #define PG8_BAR __builtin_amdgcn_s_barrier()
; #define PG8_SCHED __builtin_amdgcn_sched_barrier(0)
; template <class Epi, class Sched, bool ALIGN_EPI = false, bool SP2 = false>
; __device__ __forceinline__ void gemm_phase(PG8_LAS unsigned char* lds, const Gemm g, const Sched& S, const Epi& E) {
;     ...
;             PG8_WAIT_V(8); PG8_WAIT_L(0); PG8_BAR; PG8_MMA(0, 0, At, B0); PG8_MMA(0, 1, At, B1); PG8_BAR; PG8_SCHED;
;             PG8_LDA(At, 0, 1); PG8_STAGE(PG8_SB(0, 0), b2, voffB); PG8_STAGE(PG8_SB(0, 1), b2 + hstep, voffB); PG8_STAGE(PG8_SA(0, 0), a2, voffA);
;             PG8_WAIT_V(8); PG8_WAIT_L(0); PG8_BAR; PG8_MMA(1, 0, At, B0); PG8_MMA(1, 1, At, B1); PG8_BAR; PG8_SCHED;
;             PG8_LDB(B0, 1, 0); PG8_LDB(B1, 1, 1); PG8_SCHED; PG8_LDA(At, 1, 0); PG8_STAGE(PG8_SA(0, 1), a2 + hstep, voffA);
;             PG8_WAIT_V(8); PG8_WAIT_L(0); PG8_BAR; PG8_MMA(0, 0, At, B0); PG8_MMA(0, 1, At, B1); PG8_BAR; PG8_SCHED;
	s_waitcnt lgkmcnt(0)
	v_mfma_f32_16x16x32_bf16 v[64:67], v[124:127], v[186:189], 0
	v_mfma_f32_16x16x32_bf16 v[60:63], v[140:143], v[186:189], 0
	v_mfma_f32_16x16x32_bf16 v[48:51], v[124:127], v[194:197], 0
	v_mfma_f32_16x16x32_bf16 v[44:47], v[140:143], v[194:197], 0
	v_mfma_f32_16x16x32_bf16 v[32:35], v[124:127], v[216:219], 0
	v_mfma_f32_16x16x32_bf16 v[28:31], v[140:143], v[216:219], 0
	v_mfma_f32_16x16x32_bf16 v[16:19], v[124:127], v[224:227], 0
	v_mfma_f32_16x16x32_bf16 v[12:15], v[140:143], v[224:227], 0
	v_mfma_f32_16x16x32_bf16 v[64:67], v[136:139], v[190:193], v[64:67]
	v_mfma_f32_16x16x32_bf16 v[60:63], v[144:147], v[190:193], v[60:63]
	v_mfma_f32_16x16x32_bf16 v[48:51], v[136:139], v[198:201], v[48:51]
	v_mfma_f32_16x16x32_bf16 v[44:47], v[144:147], v[198:201], v[44:47]
	v_mfma_f32_16x16x32_bf16 v[32:35], v[136:139], v[220:223], v[32:35]
	v_mfma_f32_16x16x32_bf16 v[28:31], v[144:147], v[220:223], v[28:31]
	v_mfma_f32_16x16x32_bf16 v[16:19], v[136:139], v[228:231], v[16:19]
	v_mfma_f32_16x16x32_bf16 v[12:15], v[144:147], v[228:231], v[12:15]
	v_mfma_f32_16x16x32_bf16 v[56:59], v[148:151], v[186:189], 0
	v_mfma_f32_16x16x32_bf16 v[52:55], v[156:159], v[186:189], 0
	v_mfma_f32_16x16x32_bf16 v[40:43], v[148:151], v[194:197], 0
	v_mfma_f32_16x16x32_bf16 v[36:39], v[156:159], v[194:197], 0
	v_mfma_f32_16x16x32_bf16 v[24:27], v[148:151], v[216:219], 0
	v_mfma_f32_16x16x32_bf16 v[20:23], v[156:159], v[216:219], 0
	v_mfma_f32_16x16x32_bf16 v[8:11], v[148:151], v[224:227], 0
	v_mfma_f32_16x16x32_bf16 v[4:7], v[156:159], v[224:227], 0
	v_mfma_f32_16x16x32_bf16 v[56:59], v[152:155], v[190:193], v[56:59]
	v_mfma_f32_16x16x32_bf16 v[52:55], v[182:185], v[190:193], v[52:55]
	v_mfma_f32_16x16x32_bf16 v[40:43], v[152:155], v[198:201], v[40:43]
	v_mfma_f32_16x16x32_bf16 v[36:39], v[182:185], v[198:201], v[36:39]
	v_mfma_f32_16x16x32_bf16 v[24:27], v[152:155], v[220:223], v[24:27]
	v_mfma_f32_16x16x32_bf16 v[20:23], v[182:185], v[220:223], v[20:23]
	v_mfma_f32_16x16x32_bf16 v[8:11], v[152:155], v[228:231], v[8:11]
	v_mfma_f32_16x16x32_bf16 v[4:7], v[182:185], v[228:231], v[4:7]
	s_barrier
	s_add_i32 s68, 0, 0x18000
	s_add_i32 s69, 0, 0x1c000
	ds_read_b128 v[124:127], v170
	ds_read_b128 v[136:139], v170 offset:1024
	ds_read_b128 v[140:143], v170 offset:2048
	ds_read_b128 v[144:147], v170 offset:3072
	ds_read_b128 v[148:151], v171
	ds_read_b128 v[152:155], v171 offset:1024
	ds_read_b128 v[156:159], v171 offset:2048
	ds_read_b128 v[182:185], v171 offset:3072
	s_add_u32 s46, s46, 0x160000
	s_addc_u32 s47, s47, 0
	s_mov_b32 m0, s51
	ds_read_b128 v[186:189], v214 offset:32768
	ds_read_b128 v[190:193], v214 offset:33792
	ds_read_b128 v[194:197], v214 offset:34816
	ds_read_b128 v[198:201], v214 offset:35840
	ds_read_b128 v[216:219], v214 offset:36864
	ds_read_b128 v[220:223], v214 offset:37888
	ds_read_b128 v[224:227], v214 offset:38912
	ds_read_b128 v[228:231], v214 offset:39936
	global_load_lds_dwordx4 v176, s[46:47]
	s_mov_b32 m0, s52
	s_nop 0
	global_load_lds_dwordx4 v172, s[46:47]
	s_waitcnt vmcnt(8)
	s_waitcnt lgkmcnt(0)
	s_barrier
	s_waitcnt lgkmcnt(0)
	v_mfma_f32_16x16x32_bf16 v[132:135], v[124:127], v[186:189], v[132:135]
	v_mfma_f32_16x16x32_bf16 v[128:131], v[140:143], v[186:189], v[128:131]
	v_mfma_f32_16x16x32_bf16 v[112:115], v[124:127], v[194:197], v[112:115]
	v_mfma_f32_16x16x32_bf16 v[108:111], v[140:143], v[194:197], v[108:111]
	v_mfma_f32_16x16x32_bf16 v[96:99], v[124:127], v[216:219], v[96:99]
	v_mfma_f32_16x16x32_bf16 v[92:95], v[140:143], v[216:219], v[92:95]
	v_mfma_f32_16x16x32_bf16 v[80:83], v[124:127], v[224:227], v[80:83]
	v_mfma_f32_16x16x32_bf16 v[76:79], v[140:143], v[224:227], v[76:79]
	v_mfma_f32_16x16x32_bf16 v[132:135], v[136:139], v[190:193], v[132:135]
	v_mfma_f32_16x16x32_bf16 v[128:131], v[144:147], v[190:193], v[128:131]
	v_mfma_f32_16x16x32_bf16 v[112:115], v[136:139], v[198:201], v[112:115]
	v_mfma_f32_16x16x32_bf16 v[108:111], v[144:147], v[198:201], v[108:111]
	v_mfma_f32_16x16x32_bf16 v[96:99], v[136:139], v[220:223], v[96:99]
	v_mfma_f32_16x16x32_bf16 v[92:95], v[144:147], v[220:223], v[92:95]
	v_mfma_f32_16x16x32_bf16 v[80:83], v[136:139], v[228:231], v[80:83]
	v_mfma_f32_16x16x32_bf16 v[76:79], v[144:147], v[228:231], v[76:79]
	v_mfma_f32_16x16x32_bf16 v[120:123], v[148:151], v[186:189], v[120:123]
	v_mfma_f32_16x16x32_bf16 v[116:119], v[156:159], v[186:189], v[116:119]
	v_mfma_f32_16x16x32_bf16 v[104:107], v[148:151], v[194:197], v[104:107]
	v_mfma_f32_16x16x32_bf16 v[100:103], v[156:159], v[194:197], v[100:103]
	v_mfma_f32_16x16x32_bf16 v[88:91], v[148:151], v[216:219], v[88:91]
	v_mfma_f32_16x16x32_bf16 v[84:87], v[156:159], v[216:219], v[84:87]
	v_mfma_f32_16x16x32_bf16 v[72:75], v[148:151], v[224:227], v[72:75]
	v_mfma_f32_16x16x32_bf16 v[68:71], v[156:159], v[224:227], v[68:71]
	v_mfma_f32_16x16x32_bf16 v[120:123], v[152:155], v[190:193], v[120:123]
	v_mfma_f32_16x16x32_bf16 v[116:119], v[182:185], v[190:193], v[116:119]
	v_mfma_f32_16x16x32_bf16 v[104:107], v[152:155], v[198:201], v[104:107]
	v_mfma_f32_16x16x32_bf16 v[100:103], v[182:185], v[198:201], v[100:103]
	v_mfma_f32_16x16x32_bf16 v[88:91], v[152:155], v[220:223], v[88:91]
	v_mfma_f32_16x16x32_bf16 v[84:87], v[182:185], v[220:223], v[84:87]
	v_mfma_f32_16x16x32_bf16 v[72:75], v[152:155], v[228:231], v[72:75]
	v_mfma_f32_16x16x32_bf16 v[68:71], v[182:185], v[228:231], v[68:71]
	s_barrier
; #define PG8_STAGE(bufoff, gbase, voff) do { _Pragma("unroll") for (int _i = 0; _i < 2; ++_i) \
;         __builtin_amdgcn_global_load_lds((const unsigned*)((const char*)(gbase) + (voff)[_i]), (PG8_LAS unsigned*)(lds + (bufoff) + ldsw + _i * 8192), 16, 0, 0); } while (0)
; #define PG8_LDA(dst, b, h) do { _Pragma("unroll") for (int m = 0; m < 4; ++m) _Pragma("unroll") for (int k = 0; k < 2; ++k) dst[m][k] = *(const PG8_LAS bf16x8*)(lds + PG8_SA(b, h) + aoff + m * 2048 + k * 1024); } while (0)
; #define PG8_MMA(ai, bj, At, Bt) do { __builtin_amdgcn_s_setprio(1); _Pragma("unroll") for (int m = 0; m < 4; ++m) _Pragma("unroll") for (int n = 0; n < 2; ++n) _Pragma("unroll") for (int k = 0; k < 2; ++k) \
;         acc[ai][bj][m][n] = __builtin_amdgcn_mfma_f32_16x16x32_bf16(Bt[n][k], At[m][k], acc[ai][bj][m][n], 0, 0, 0); __builtin_amdgcn_s_setprio(0); } while (0)
; #define PG8_WAIT_V(n) asm volatile("s_waitcnt vmcnt(" #n ")" ::: "memory")
; #define PG8_WAIT_L(n) asm volatile("s_waitcnt lgkmcnt(" #n ")" ::: "memory")
; #define PG8_BAR __builtin_amdgcn_s_barrier()
; #define PG8_SCHED __builtin_amdgcn_sched_barrier(0)
; template <class Epi, class Sched, bool ALIGN_EPI = false, bool SP2 = false>
; __device__ __forceinline__ void gemm_phase(PG8_LAS unsigned char* lds, const Gemm g, const Sched& S, const Epi& E) {
;     ...
;             PG8_LDA(At, 1, 1); PG8_STAGE(PG8_SB(1, 0), b3, voffB); PG8_STAGE(PG8_SB(1, 1), b3 + hstep, voffB); PG8_STAGE(PG8_SA(1, 0), a3, voffA);
;             PG8_WAIT_V(8); PG8_WAIT_L(0); PG8_BAR; PG8_MMA(1, 0, At, B0); PG8_MMA(1, 1, At, B1); PG8_BAR; PG8_SCHED;
	s_add_i32 s46, s68, s48
	s_mov_b32 m0, s46
	ds_read_b128 v[186:189], v214 offset:49152
	ds_read_b128 v[190:193], v214 offset:50176
	ds_read_b128 v[194:197], v214 offset:51200
	ds_read_b128 v[198:201], v214 offset:52224
	ds_read_b128 v[216:219], v214 offset:53248
	ds_read_b128 v[220:223], v214 offset:54272
	ds_read_b128 v[224:227], v214 offset:55296
	ds_read_b128 v[228:231], v214 offset:56320
	global_load_lds_dwordx4 v174, s[98:99]
	s_add_i32 m0, s46, 0x2000
	s_add_u32 s38, s38, 0x160080
	s_addc_u32 s39, s39, 0
	s_add_i32 s46, s69, s48
	global_load_lds_dwordx4 v0, s[98:99]
	s_mov_b32 m0, s46
	s_nop 0
	global_load_lds_dwordx4 v174, s[38:39]
	s_add_i32 m0, s46, 0x2000
	s_nop 0
	global_load_lds_dwordx4 v0, s[38:39]
	s_mov_b32 m0, s53
	s_nop 0
	global_load_lds_dwordx4 v176, s[100:101]
	s_mov_b32 m0, s57
	s_nop 0
	global_load_lds_dwordx4 v172, s[100:101]
	s_waitcnt vmcnt(8)
	s_waitcnt lgkmcnt(0)
	s_barrier
	s_waitcnt lgkmcnt(0)
	v_mfma_f32_16x16x32_bf16 v[64:67], v[124:127], v[186:189], v[64:67]
	v_mfma_f32_16x16x32_bf16 v[60:63], v[140:143], v[186:189], v[60:63]
	v_mfma_f32_16x16x32_bf16 v[48:51], v[124:127], v[194:197], v[48:51]
	v_mfma_f32_16x16x32_bf16 v[44:47], v[140:143], v[194:197], v[44:47]
	v_mfma_f32_16x16x32_bf16 v[32:35], v[124:127], v[216:219], v[32:35]
	v_mfma_f32_16x16x32_bf16 v[28:31], v[140:143], v[216:219], v[28:31]
	v_mfma_f32_16x16x32_bf16 v[16:19], v[124:127], v[224:227], v[16:19]
	v_mfma_f32_16x16x32_bf16 v[12:15], v[140:143], v[224:227], v[12:15]
	v_mfma_f32_16x16x32_bf16 v[64:67], v[136:139], v[190:193], v[64:67]
	v_mfma_f32_16x16x32_bf16 v[60:63], v[144:147], v[190:193], v[60:63]
	v_mfma_f32_16x16x32_bf16 v[48:51], v[136:139], v[198:201], v[48:51]
	v_mfma_f32_16x16x32_bf16 v[44:47], v[144:147], v[198:201], v[44:47]
	v_mfma_f32_16x16x32_bf16 v[32:35], v[136:139], v[220:223], v[32:35]
	v_mfma_f32_16x16x32_bf16 v[28:31], v[144:147], v[220:223], v[28:31]
	v_mfma_f32_16x16x32_bf16 v[16:19], v[136:139], v[228:231], v[16:19]
	v_mfma_f32_16x16x32_bf16 v[12:15], v[144:147], v[228:231], v[12:15]
	v_mfma_f32_16x16x32_bf16 v[56:59], v[148:151], v[186:189], v[56:59]
	v_mfma_f32_16x16x32_bf16 v[52:55], v[156:159], v[186:189], v[52:55]
	v_mfma_f32_16x16x32_bf16 v[40:43], v[148:151], v[194:197], v[40:43]
	v_mfma_f32_16x16x32_bf16 v[36:39], v[156:159], v[194:197], v[36:39]
	v_mfma_f32_16x16x32_bf16 v[24:27], v[148:151], v[216:219], v[24:27]
	v_mfma_f32_16x16x32_bf16 v[20:23], v[156:159], v[216:219], v[20:23]
	v_mfma_f32_16x16x32_bf16 v[8:11], v[148:151], v[224:227], v[8:11]
	v_mfma_f32_16x16x32_bf16 v[4:7], v[156:159], v[224:227], v[4:7]
	v_mfma_f32_16x16x32_bf16 v[56:59], v[152:155], v[190:193], v[56:59]
	v_mfma_f32_16x16x32_bf16 v[52:55], v[182:185], v[190:193], v[52:55]
	v_mfma_f32_16x16x32_bf16 v[40:43], v[152:155], v[198:201], v[40:43]
	v_mfma_f32_16x16x32_bf16 v[36:39], v[182:185], v[198:201], v[36:39]
	v_mfma_f32_16x16x32_bf16 v[24:27], v[152:155], v[220:223], v[24:27]
	v_mfma_f32_16x16x32_bf16 v[20:23], v[182:185], v[220:223], v[20:23]
	v_mfma_f32_16x16x32_bf16 v[8:11], v[152:155], v[228:231], v[8:11]
	v_mfma_f32_16x16x32_bf16 v[4:7], v[182:185], v[228:231], v[4:7]
	s_barrier
	s_add_i32 s67, s67, 2
	s_add_u32 s2, s2, 0x100
	s_addc_u32 s3, s3, 0
	s_cmpk_gt_u32 s67, 0x55
